# scan: staging waves yield the SIMD (s_sleep 4) right after the chunk barrier so the scan waves' chunk prologue issues unimpeded
# speedup vs baseline: 1.0037x; 1.0037x over previous
; #define UFOR(v, n) _Pragma("unroll") for (int v = 0; v < (n); ++v)
; __device__ __forceinline__ float h2f(u16 u) { _Float16 h = __builtin_bit_cast(_Float16, u); return (float)h; }
; __device__ __forceinline__ void phase_scan(KP p) {
;     ...
;       if (w >= 4) {
;         if (((c + 1) & 1) == ppair) {
;           if (c + 1 < NCH) {
;             const int buf = (c + 1) & 1;
;             UFOR(e, 2) {
;               const int q = pt + 128 * e, st = q >> 3, g8 = q & 7;
;               float f[8];
;               float* fd = feat + ((buf * 32 + st) * 5) * 64 + g8 * 8;
;               unpack8(rq[e][0], f); *(float4*)(fd) = make_float4(f[0], f[1], f[2], f[3]); *(float4*)(fd + 4) = make_float4(f[4], f[5], f[6], f[7]);
;               { const uint4 u = rq[e][1];
;                 f[0] = h2f((u16)(u.x & 0xffff)); f[1] = h2f((u16)(u.x >> 16)); f[2] = h2f((u16)(u.y & 0xffff)); f[3] = h2f((u16)(u.y >> 16));
;                 f[4] = h2f((u16)(u.z & 0xffff)); f[5] = h2f((u16)(u.z >> 16)); f[6] = h2f((u16)(u.w & 0xffff)); f[7] = h2f((u16)(u.w >> 16));
;                 UFOR(x, 8) f[x] = __expf(-f[x]);
;                 *(float4*)(fd + 64) = make_float4(f[0], f[1], f[2], f[3]); *(float4*)(fd + 68) = make_float4(f[4], f[5], f[6], f[7]); }
;               unpack8(rq[e][2], f); *(float4*)(fd + 128) = make_float4(f[0], f[1], f[2], f[3]); *(float4*)(fd + 132) = make_float4(f[4], f[5], f[6], f[7]);
;               unpack8(rq[e][3], f); *(float4*)(fd + 192) = make_float4(-f[0], -f[1], -f[2], -f[3]); *(float4*)(fd + 196) = make_float4(-f[4], -f[5], -f[6], -f[7]);
;               unpack8(rq[e][4], f); *(float4*)(fd + 256) = make_float4(f[0], f[1], f[2], f[3]); *(float4*)(fd + 260) = make_float4(f[4], f[5], f[6], f[7]);
;               if ((g8 >> 1) == rg) {
;                 unpack8(rq[e][5], f);
;                 float* vd = vbuf + (buf * 16 + (g8 & 1) * 8) * 32 + st;
;                 UFOR(x, 8) vd[x * 32] = f[x];
;               }
.LBB0_756:
	s_and_saveexec_b64 s[50:51], vcc
	s_xor_b64 s[70:71], exec, s[50:51]
	s_cbranch_execz .LBB0_770
	s_sleep 4
	v_xor_b32_e32 v48, s18, v111
	v_and_b32_e32 v48, 1, v48
	v_cmp_eq_u32_e64 s[50:51], 1, v48
	s_and_saveexec_b64 s[72:73], s[50:51]
	s_xor_b64 s[72:73], exec, s[72:73]
	s_cbranch_execz .LBB0_766
	s_cmpk_eq_i32 s18, 0x207
	s_cbranch_scc1 .LBB0_764
	s_waitcnt vmcnt(0)
	v_and_b32_e32 v56, 7, v135
	v_bfe_u32 v57, v135, 3, 4
	v_bfe_u32 v58, v135, 7, 1
	v_lshl_add_u32 v57, v58, 5, v57
	v_mul_u32_u24_e32 v57, 0x220, v57
	v_lshrrev_b32_e32 v58, 2, v56
	v_and_b32_e32 v56, 3, v56
	v_lshlrev_b32_e32 v58, 4, v58
	v_lshl_add_u32 v56, v56, 2, v58
	s_mov_b32 s74, 0x16000
	v_add3_u32 v64, v57, v56, s74
	v_add_u32_e32 v65, 0x2200, v64
	s_mov_b32 s74, 0x5040100
	s_mov_b32 s75, 0x7060302
	v_perm_b32 v60, v6, v4, s74
	v_perm_b32 v61, v6, v4, s75
	v_perm_b32 v62, v7, v5, s74
	v_perm_b32 v63, v7, v5, s75
	ds_write2_b32 v64, v60, v61 offset0:0 offset1:8
	ds_write2_b32 v64, v62, v63 offset0:16 offset1:24
	v_perm_b32 v60, v10, v8, s74
	v_perm_b32 v61, v10, v8, s75
	v_perm_b32 v62, v11, v9, s74
	v_perm_b32 v63, v11, v9, s75
	ds_write2_b32 v64, v60, v61 offset0:32 offset1:40
	ds_write2_b32 v64, v62, v63 offset0:48 offset1:56
	v_perm_b32 v60, v14, v12, s74
	v_perm_b32 v61, v14, v12, s75
	v_perm_b32 v62, v15, v13, s74
	v_perm_b32 v63, v15, v13, s75
	v_xor_b32_e32 v60, 0x80008000, v60
	v_xor_b32_e32 v61, 0x80008000, v61
	v_xor_b32_e32 v62, 0x80008000, v62
	v_xor_b32_e32 v63, 0x80008000, v63
	ds_write2_b32 v64, v60, v61 offset0:64 offset1:72
	ds_write2_b32 v64, v62, v63 offset0:80 offset1:88
	v_perm_b32 v60, v18, v16, s74
	v_perm_b32 v61, v18, v16, s75
	v_perm_b32 v62, v19, v17, s74
	v_perm_b32 v63, v19, v17, s75
	ds_write2_b32 v64, v60, v61 offset0:96 offset1:104
	ds_write2_b32 v64, v62, v63 offset0:112 offset1:120
	v_cvt_f32_f16_e32 v48, v0
	v_cvt_f32_f16_sdwa v49, v0 dst_sel:DWORD dst_unused:UNUSED_PAD src0_sel:WORD_1
	v_cvt_f32_f16_e32 v50, v1
	v_cvt_f32_f16_sdwa v51, v1 dst_sel:DWORD dst_unused:UNUSED_PAD src0_sel:WORD_1
	v_cvt_f32_f16_e32 v52, v2
	v_cvt_f32_f16_sdwa v53, v2 dst_sel:DWORD dst_unused:UNUSED_PAD src0_sel:WORD_1
	v_cvt_f32_f16_e32 v54, v3
	v_cvt_f32_f16_sdwa v55, v3 dst_sel:DWORD dst_unused:UNUSED_PAD src0_sel:WORD_1
	v_mul_f32_e32 v48, 0xbfb8aa3b, v48
	v_mul_f32_e32 v49, 0xbfb8aa3b, v49
	v_mul_f32_e32 v50, 0xbfb8aa3b, v50
	v_mul_f32_e32 v51, 0xbfb8aa3b, v51
	v_exp_f32_e32 v48, v48
	v_exp_f32_e32 v49, v49
	v_exp_f32_e32 v50, v50
	v_exp_f32_e32 v51, v51
	v_mul_f32_e32 v52, 0xbfb8aa3b, v52
	v_mul_f32_e32 v53, 0xbfb8aa3b, v53
	v_mul_f32_e32 v54, 0xbfb8aa3b, v54
	v_mul_f32_e32 v55, 0xbfb8aa3b, v55
	v_exp_f32_e32 v52, v52
	v_exp_f32_e32 v53, v53
	v_exp_f32_e32 v54, v54
	v_exp_f32_e32 v55, v55
	ds_write_b128 v149, v[48:51] offset:256
	ds_write_b128 v149, v[52:55] offset:272
	s_and_saveexec_b64 s[50:51], s[48:49]
	s_cbranch_execz .LBB0_761
	v_lshlrev_b32_e32 v48, 16, v20
	v_and_b32_e32 v49, 0xffff0000, v20
	v_lshlrev_b32_e32 v50, 16, v21
	v_and_b32_e32 v51, 0xffff0000, v21
	v_lshlrev_b32_e32 v52, 16, v22
	v_and_b32_e32 v53, 0xffff0000, v22
	v_lshlrev_b32_e32 v54, 16, v23
	v_and_b32_e32 v55, 0xffff0000, v23
	ds_write2_b32 v130, v48, v49 offset1:32
	ds_write2_b32 v130, v50, v51 offset0:64 offset1:96
	ds_write2_b32 v130, v52, v53 offset0:128 offset1:160
	ds_write2_b32 v130, v54, v55 offset0:192 offset1:224
